# gate/up GEMM epilogue rewritten by hand: same arithmetic, rstd reads via immediate LDS offsets, incremental store addresses (on v11)
# speedup vs baseline: 1.0079x; 1.0058x over previous
.LBB0_232:
	ds_read_b128 v[158:161], v152
	ds_read_b128 v[162:165], v152 offset:1024
	ds_read_b128 v[166:169], v152 offset:2048
	ds_read_b128 v[170:173], v152 offset:3072
	s_mov_b32 m0, s47
	v_lshl_add_u64 v[206:207], v[142:143], 0, s[34:35]
	ds_read_b128 v[174:177], v153
	ds_read_b128 v[178:181], v153 offset:1024
	ds_read_b128 v[182:185], v153 offset:2048
	ds_read_b128 v[186:189], v153 offset:3072
	ds_read_b128 v[190:193], v153 offset:4096
	ds_read_b128 v[194:197], v153 offset:5120
	ds_read_b128 v[198:201], v153 offset:6144
	ds_read_b128 v[202:205], v153 offset:7168
	global_load_lds_dwordx4 v[206:207], off
	s_mov_b32 m0, s48
	v_lshl_add_u64 v[206:207], v[144:145], 0, s[34:35]
	global_load_lds_dwordx4 v[206:207], off
	s_waitcnt lgkmcnt(8)
	s_barrier
	s_waitcnt lgkmcnt(0)
	v_mfma_f32_16x16x32_bf16 v[120:123], v[158:161], v[174:177], v[120:123]
	s_add_i32 s61, s34, 0xfffc0080
	v_mfma_f32_16x16x32_bf16 v[112:115], v[166:169], v[174:177], v[112:115]
	s_cmp_eq_u32 s19, 12
	v_mfma_f32_16x16x32_bf16 v[104:107], v[158:161], v[182:185], v[104:107]
	s_cselect_b64 s[36:37], -1, 0
	v_mfma_f32_16x16x32_bf16 v[96:99], v[166:169], v[182:185], v[96:99]
	s_and_b64 s[62:63], s[36:37], exec
	v_mfma_f32_16x16x32_bf16 v[88:91], v[158:161], v[190:193], v[88:91]
	s_cselect_b32 s61, 0, s61
	v_mfma_f32_16x16x32_bf16 v[80:83], v[166:169], v[190:193], v[80:83]
	s_and_b64 s[36:37], s[30:31], s[36:37]
	v_mfma_f32_16x16x32_bf16 v[72:75], v[158:161], v[198:201], v[72:75]
	s_and_b64 s[36:37], s[36:37], exec
	v_mfma_f32_16x16x32_bf16 v[60:63], v[166:169], v[198:201], v[60:63]
	s_cselect_b32 s63, s21, s27
	v_mfma_f32_16x16x32_bf16 v[120:123], v[162:165], v[178:181], v[120:123]
	s_cselect_b32 s62, s20, s26
	v_mfma_f32_16x16x32_bf16 v[112:115], v[170:173], v[178:181], v[112:115]
	s_cselect_b32 s37, s23, s29
	v_mfma_f32_16x16x32_bf16 v[104:107], v[162:165], v[186:189], v[104:107]
	s_cselect_b32 s36, s22, s28
	v_mfma_f32_16x16x32_bf16 v[96:99], v[170:173], v[186:189], v[96:99]
	v_mfma_f32_16x16x32_bf16 v[88:91], v[162:165], v[194:197], v[88:91]
	v_mfma_f32_16x16x32_bf16 v[80:83], v[170:173], v[194:197], v[80:83]
	v_mfma_f32_16x16x32_bf16 v[72:75], v[162:165], v[202:205], v[72:75]
	v_mfma_f32_16x16x32_bf16 v[60:63], v[170:173], v[202:205], v[60:63]
	s_barrier
	s_add_u32 s36, s36, s61
	s_addc_u32 s37, s37, 0
	s_mov_b32 m0, s49
	v_lshl_add_u64 v[218:219], s[36:37], 0, v[134:135]
	ds_read_b128 v[206:209], v154
	ds_read_b128 v[210:213], v154 offset:1024
	ds_read_b128 v[214:217], v154 offset:2048
	ds_read_b128 v[222:225], v154 offset:3072
	global_load_lds_dwordx4 v[218:219], off
	s_mov_b32 m0, s50
	v_lshl_add_u64 v[226:227], s[36:37], 0, v[130:131]
	global_load_lds_dwordx4 v[226:227], off
	s_barrier
	s_waitcnt lgkmcnt(0)
	v_mfma_f32_16x16x32_bf16 v[124:127], v[206:209], v[174:177], v[124:127]
	v_mfma_f32_16x16x32_bf16 v[116:119], v[214:217], v[174:177], v[116:119]
	v_mfma_f32_16x16x32_bf16 v[108:111], v[206:209], v[182:185], v[108:111]
	v_mfma_f32_16x16x32_bf16 v[100:103], v[214:217], v[182:185], v[100:103]
	v_mfma_f32_16x16x32_bf16 v[92:95], v[206:209], v[190:193], v[92:95]
	v_mfma_f32_16x16x32_bf16 v[84:87], v[214:217], v[190:193], v[84:87]
	v_mfma_f32_16x16x32_bf16 v[76:79], v[206:209], v[198:201], v[76:79]
	v_mfma_f32_16x16x32_bf16 v[64:67], v[214:217], v[198:201], v[64:67]
	v_mfma_f32_16x16x32_bf16 v[124:127], v[210:213], v[178:181], v[124:127]
	v_mfma_f32_16x16x32_bf16 v[116:119], v[222:225], v[178:181], v[116:119]
	v_mfma_f32_16x16x32_bf16 v[108:111], v[210:213], v[186:189], v[108:111]
	v_mfma_f32_16x16x32_bf16 v[100:103], v[222:225], v[186:189], v[100:103]
	v_mfma_f32_16x16x32_bf16 v[92:95], v[210:213], v[194:197], v[92:95]
	v_mfma_f32_16x16x32_bf16 v[84:87], v[222:225], v[194:197], v[84:87]
	v_mfma_f32_16x16x32_bf16 v[76:79], v[210:213], v[202:205], v[76:79]
	v_mfma_f32_16x16x32_bf16 v[64:67], v[222:225], v[202:205], v[64:67]
	s_add_u32 s62, s62, s61
	s_addc_u32 s63, s63, 0
	s_mov_b32 m0, s25
	v_lshl_add_u64 v[228:229], s[62:63], 0, v[136:137]
	s_barrier
	ds_read_b128 v[174:177], v153 offset:16384
	ds_read_b128 v[178:181], v153 offset:17408
	ds_read_b128 v[182:185], v153 offset:18432
	ds_read_b128 v[186:189], v153 offset:19456
	ds_read_b128 v[190:193], v153 offset:20480
	ds_read_b128 v[194:197], v153 offset:21504
	ds_read_b128 v[198:201], v153 offset:22528
	ds_read_b128 v[202:205], v153 offset:23552
	global_load_lds_dwordx4 v[228:229], off
	s_mov_b32 m0, s41
	v_lshl_add_u64 v[230:231], s[62:63], 0, v[132:133]
	global_load_lds_dwordx4 v[230:231], off
	s_barrier
	s_waitcnt lgkmcnt(0)
	v_mfma_f32_16x16x32_bf16 v[56:59], v[158:161], v[174:177], v[56:59]
	v_mfma_f32_16x16x32_bf16 v[48:51], v[166:169], v[174:177], v[48:51]
	v_mfma_f32_16x16x32_bf16 v[40:43], v[158:161], v[182:185], v[40:43]
	v_mfma_f32_16x16x32_bf16 v[32:35], v[166:169], v[182:185], v[32:35]
	v_mfma_f32_16x16x32_bf16 v[24:27], v[158:161], v[190:193], v[24:27]
	v_mfma_f32_16x16x32_bf16 v[16:19], v[166:169], v[190:193], v[16:19]
	v_mfma_f32_16x16x32_bf16 v[8:11], v[158:161], v[198:201], v[8:11]
	v_mfma_f32_16x16x32_bf16 v[0:3], v[166:169], v[198:201], v[0:3]
	v_mfma_f32_16x16x32_bf16 v[56:59], v[162:165], v[178:181], v[56:59]
	v_mfma_f32_16x16x32_bf16 v[48:51], v[170:173], v[178:181], v[48:51]
	v_mfma_f32_16x16x32_bf16 v[40:43], v[162:165], v[186:189], v[40:43]
	v_mfma_f32_16x16x32_bf16 v[32:35], v[170:173], v[186:189], v[32:35]
	v_mfma_f32_16x16x32_bf16 v[24:27], v[162:165], v[194:197], v[24:27]
	v_mfma_f32_16x16x32_bf16 v[16:19], v[170:173], v[194:197], v[16:19]
	v_mfma_f32_16x16x32_bf16 v[8:11], v[162:165], v[202:205], v[8:11]
	v_mfma_f32_16x16x32_bf16 v[0:3], v[170:173], v[202:205], v[0:3]
	s_barrier
	s_add_u32 s64, s36, 0x40000
	s_addc_u32 s65, s37, 0
	s_mov_b32 m0, s55
	v_lshl_add_u64 v[158:159], s[64:65], 0, v[134:135]
	global_load_lds_dwordx4 v[158:159], off
	s_mov_b32 m0, s56
	v_lshl_add_u64 v[158:159], s[64:65], 0, v[130:131]
	global_load_lds_dwordx4 v[158:159], off
	s_waitcnt vmcnt(6)
	s_barrier
	v_mfma_f32_16x16x32_bf16 v[68:71], v[206:209], v[174:177], v[68:71]
	v_mfma_f32_16x16x32_bf16 v[52:55], v[214:217], v[174:177], v[52:55]
	v_mfma_f32_16x16x32_bf16 v[44:47], v[206:209], v[182:185], v[44:47]
	v_mfma_f32_16x16x32_bf16 v[36:39], v[214:217], v[182:185], v[36:39]
	v_mfma_f32_16x16x32_bf16 v[28:31], v[206:209], v[190:193], v[28:31]
	v_mfma_f32_16x16x32_bf16 v[20:23], v[214:217], v[190:193], v[20:23]
	v_mfma_f32_16x16x32_bf16 v[12:15], v[206:209], v[198:201], v[12:15]
	v_mfma_f32_16x16x32_bf16 v[4:7], v[214:217], v[198:201], v[4:7]
	v_mfma_f32_16x16x32_bf16 v[68:71], v[210:213], v[178:181], v[68:71]
	v_mfma_f32_16x16x32_bf16 v[52:55], v[222:225], v[178:181], v[52:55]
	v_mfma_f32_16x16x32_bf16 v[44:47], v[210:213], v[186:189], v[44:47]
	v_mfma_f32_16x16x32_bf16 v[36:39], v[222:225], v[186:189], v[36:39]
	v_mfma_f32_16x16x32_bf16 v[28:31], v[210:213], v[194:197], v[28:31]
	v_mfma_f32_16x16x32_bf16 v[20:23], v[222:225], v[194:197], v[20:23]
	v_mfma_f32_16x16x32_bf16 v[12:15], v[210:213], v[202:205], v[12:15]
	v_mfma_f32_16x16x32_bf16 v[4:7], v[222:225], v[202:205], v[4:7]
	s_barrier
	ds_read_b128 v[158:161], v155
	ds_read_b128 v[162:165], v155 offset:1024
	ds_read_b128 v[166:169], v155 offset:2048
	ds_read_b128 v[170:173], v155 offset:3072
	s_add_u32 s62, s62, 0x40000
	s_addc_u32 s63, s63, 0
	s_mov_b32 m0, s42
	v_lshl_add_u64 v[206:207], s[62:63], 0, v[136:137]
	ds_read_b128 v[174:177], v153 offset:32768
	ds_read_b128 v[178:181], v153 offset:33792
	ds_read_b128 v[182:185], v153 offset:34816
	ds_read_b128 v[186:189], v153 offset:35840
	ds_read_b128 v[190:193], v153 offset:36864
	ds_read_b128 v[194:197], v153 offset:37888
	ds_read_b128 v[198:201], v153 offset:38912
	ds_read_b128 v[202:205], v153 offset:39936
	global_load_lds_dwordx4 v[206:207], off
	s_mov_b32 m0, s43
	v_lshl_add_u64 v[206:207], s[62:63], 0, v[132:133]
	global_load_lds_dwordx4 v[206:207], off
	s_waitcnt lgkmcnt(8)
	s_barrier
	s_waitcnt lgkmcnt(0)
	v_mfma_f32_16x16x32_bf16 v[120:123], v[158:161], v[174:177], v[120:123]
	v_mfma_f32_16x16x32_bf16 v[112:115], v[166:169], v[174:177], v[112:115]
	v_mfma_f32_16x16x32_bf16 v[104:107], v[158:161], v[182:185], v[104:107]
	v_mfma_f32_16x16x32_bf16 v[96:99], v[166:169], v[182:185], v[96:99]
	v_mfma_f32_16x16x32_bf16 v[88:91], v[158:161], v[190:193], v[88:91]
	v_mfma_f32_16x16x32_bf16 v[80:83], v[166:169], v[190:193], v[80:83]
	v_mfma_f32_16x16x32_bf16 v[72:75], v[158:161], v[198:201], v[72:75]
	v_mfma_f32_16x16x32_bf16 v[60:63], v[166:169], v[198:201], v[60:63]
	v_mfma_f32_16x16x32_bf16 v[120:123], v[162:165], v[178:181], v[120:123]
	v_mfma_f32_16x16x32_bf16 v[112:115], v[170:173], v[178:181], v[112:115]
	v_mfma_f32_16x16x32_bf16 v[104:107], v[162:165], v[186:189], v[104:107]
	v_mfma_f32_16x16x32_bf16 v[96:99], v[170:173], v[186:189], v[96:99]
	v_mfma_f32_16x16x32_bf16 v[88:91], v[162:165], v[194:197], v[88:91]
	v_mfma_f32_16x16x32_bf16 v[80:83], v[170:173], v[194:197], v[80:83]
	v_mfma_f32_16x16x32_bf16 v[72:75], v[162:165], v[202:205], v[72:75]
	v_mfma_f32_16x16x32_bf16 v[60:63], v[170:173], v[202:205], v[60:63]
	s_barrier
	s_mov_b32 m0, s57
	v_lshl_add_u64 v[218:219], v[218:219], 0, s[6:7]
	ds_read_b128 v[206:209], v156
	ds_read_b128 v[210:213], v156 offset:1024
	ds_read_b128 v[214:217], v156 offset:2048
	ds_read_b128 v[222:225], v156 offset:3072
	global_load_lds_dwordx4 v[218:219], off
	s_mov_b32 m0, s58
	v_lshl_add_u64 v[218:219], v[226:227], 0, s[6:7]
	global_load_lds_dwordx4 v[218:219], off
	s_barrier
	s_waitcnt lgkmcnt(0)
	v_mfma_f32_16x16x32_bf16 v[124:127], v[206:209], v[174:177], v[124:127]
	v_mfma_f32_16x16x32_bf16 v[116:119], v[214:217], v[174:177], v[116:119]
	v_mfma_f32_16x16x32_bf16 v[108:111], v[206:209], v[182:185], v[108:111]
	v_mfma_f32_16x16x32_bf16 v[100:103], v[214:217], v[182:185], v[100:103]
	v_mfma_f32_16x16x32_bf16 v[92:95], v[206:209], v[190:193], v[92:95]
	v_mfma_f32_16x16x32_bf16 v[84:87], v[214:217], v[190:193], v[84:87]
	v_mfma_f32_16x16x32_bf16 v[76:79], v[206:209], v[198:201], v[76:79]
	v_mfma_f32_16x16x32_bf16 v[64:67], v[214:217], v[198:201], v[64:67]
	v_mfma_f32_16x16x32_bf16 v[124:127], v[210:213], v[178:181], v[124:127]
	v_mfma_f32_16x16x32_bf16 v[116:119], v[222:225], v[178:181], v[116:119]
	v_mfma_f32_16x16x32_bf16 v[108:111], v[210:213], v[186:189], v[108:111]
	v_mfma_f32_16x16x32_bf16 v[100:103], v[222:225], v[186:189], v[100:103]
	v_mfma_f32_16x16x32_bf16 v[92:95], v[210:213], v[194:197], v[92:95]
	v_mfma_f32_16x16x32_bf16 v[84:87], v[222:225], v[194:197], v[84:87]
	v_mfma_f32_16x16x32_bf16 v[76:79], v[210:213], v[202:205], v[76:79]
	v_mfma_f32_16x16x32_bf16 v[64:67], v[222:225], v[202:205], v[64:67]
	s_mov_b32 m0, s44
	v_lshl_add_u64 v[218:219], v[228:229], 0, s[6:7]
	s_barrier
	ds_read_b128 v[174:177], v153 offset:49152
	ds_read_b128 v[178:181], v153 offset:50176
	ds_read_b128 v[182:185], v153 offset:51200
	ds_read_b128 v[186:189], v153 offset:52224
	ds_read_b128 v[190:193], v153 offset:53248
	ds_read_b128 v[194:197], v153 offset:54272
	ds_read_b128 v[198:201], v153 offset:55296
	ds_read_b128 v[202:205], v153 offset:56320
	global_load_lds_dwordx4 v[218:219], off
	s_mov_b32 m0, s45
	v_lshl_add_u64 v[218:219], v[230:231], 0, s[6:7]
	global_load_lds_dwordx4 v[218:219], off
	s_barrier
; __device__ __forceinline__ unsigned pk2(float lo, float hi) { unsigned r; asm volatile("v_cvt_pk_bf16_f32 %0, %1, %2" : "=v"(r) : "v"(lo), "v"(hi)); return r; }
; __device__ __forceinline__ unsigned pk2(float lo, float hi) { return f2bf(lo) | (f2bf(hi) << 16); }
;     ...
;         G_PAIR(0, 1);
; #pragma unroll 1
;         for (int t = 2; t < nt; t += 2) G_PAIR(t, 0);
;     __device__ __forceinline__ void epi(const f32x4 (&acc)[2][2][4][2], const Unit& u, int wr, int wc, int fr, int fq) const {
;     ...
;         const int row0 = u.pm * 256 + wr * 64 + fr, col0 = u.pn * 128 + wc * 32 + 8 * fq;
; #pragma unroll
;         for (int ai = 0; ai < 2; ++ai)
; #pragma unroll
;             for (int m = 0; m < 4; ++m) {
;                 const int row = row0 + ai * 128 + m * 16; const float rs = rs_lds[((u.pm >> 3) & 1) * 256 + (row & 255)];
;                 const float rs2 = rs * -1.4426950408889634f, rsq = rs * rs;
;                 f32x2 v[4];
; #pragma unroll
;                 for (int n = 0; n < 2; ++n)
; #pragma unroll
;                     for (int jp = 0; jp < 2; ++jp) {
;                         const f32x2 gg = (f32x2){acc[ai][0][m][n][2 * jp], acc[ai][0][m][n][2 * jp + 1]}, uu = (f32x2){acc[ai][1][m][n][2 * jp], acc[ai][1][m][n][2 * jp + 1]};
;                         const f32x2 t = gg * rs2; f32x2 e; e.x = __builtin_amdgcn_exp2f(t.x); e.y = __builtin_amdgcn_exp2f(t.y);
;                         const f32x2 d = e + 1.0f; f32x2 r; r.x = __builtin_amdgcn_rcpf(d.x); r.y = __builtin_amdgcn_rcpf(d.y);
;                         v[n * 2 + jp] = (gg * uu) * (r * rsq);
;                     }
;                 u32x4 w; w.x = pk2(v[0].x, v[0].y); w.y = pk2(v[1].x, v[1].y); w.z = pk2(v[2].x, v[2].y); w.w = pk2(v[3].x, v[3].y);
;                 *(u32x4*)(H + (size_t)row * FF + col0) = w;
	s_waitcnt lgkmcnt(0)
	v_mfma_f32_16x16x32_bf16 v[56:59], v[158:161], v[174:177], v[56:59]
	v_mfma_f32_16x16x32_bf16 v[48:51], v[166:169], v[174:177], v[48:51]
	v_mfma_f32_16x16x32_bf16 v[40:43], v[158:161], v[182:185], v[40:43]
	v_mfma_f32_16x16x32_bf16 v[32:35], v[166:169], v[182:185], v[32:35]
	v_mfma_f32_16x16x32_bf16 v[24:27], v[158:161], v[190:193], v[24:27]
	v_mfma_f32_16x16x32_bf16 v[16:19], v[166:169], v[190:193], v[16:19]
	v_mfma_f32_16x16x32_bf16 v[8:11], v[158:161], v[198:201], v[8:11]
	v_mfma_f32_16x16x32_bf16 v[0:3], v[166:169], v[198:201], v[0:3]
	v_mfma_f32_16x16x32_bf16 v[56:59], v[162:165], v[178:181], v[56:59]
	v_mfma_f32_16x16x32_bf16 v[48:51], v[170:173], v[178:181], v[48:51]
	v_mfma_f32_16x16x32_bf16 v[40:43], v[162:165], v[186:189], v[40:43]
	v_mfma_f32_16x16x32_bf16 v[32:35], v[170:173], v[186:189], v[32:35]
	v_mfma_f32_16x16x32_bf16 v[24:27], v[162:165], v[194:197], v[24:27]
	v_mfma_f32_16x16x32_bf16 v[16:19], v[170:173], v[194:197], v[16:19]
	v_mfma_f32_16x16x32_bf16 v[8:11], v[162:165], v[202:205], v[8:11]
	v_mfma_f32_16x16x32_bf16 v[0:3], v[170:173], v[202:205], v[0:3]
	s_barrier
	s_add_u32 s36, s36, 0x40080
	s_addc_u32 s37, s37, 0
	s_mov_b32 m0, s59
	v_lshl_add_u64 v[158:159], s[36:37], 0, v[134:135]
	global_load_lds_dwordx4 v[158:159], off
	s_mov_b32 m0, s17
	v_lshl_add_u64 v[158:159], s[36:37], 0, v[130:131]
	global_load_lds_dwordx4 v[158:159], off
	s_waitcnt vmcnt(6)
	s_barrier
	v_mfma_f32_16x16x32_bf16 v[68:71], v[206:209], v[174:177], v[68:71]
	v_mfma_f32_16x16x32_bf16 v[52:55], v[214:217], v[174:177], v[52:55]
	v_mfma_f32_16x16x32_bf16 v[44:47], v[206:209], v[182:185], v[44:47]
	v_mfma_f32_16x16x32_bf16 v[36:39], v[214:217], v[182:185], v[36:39]
	v_mfma_f32_16x16x32_bf16 v[28:31], v[206:209], v[190:193], v[28:31]
	v_mfma_f32_16x16x32_bf16 v[20:23], v[214:217], v[190:193], v[20:23]
	v_mfma_f32_16x16x32_bf16 v[12:15], v[206:209], v[198:201], v[12:15]
	v_mfma_f32_16x16x32_bf16 v[4:7], v[214:217], v[198:201], v[4:7]
	v_mfma_f32_16x16x32_bf16 v[68:71], v[210:213], v[178:181], v[68:71]
	v_mfma_f32_16x16x32_bf16 v[52:55], v[222:225], v[178:181], v[52:55]
	v_mfma_f32_16x16x32_bf16 v[44:47], v[210:213], v[186:189], v[44:47]
	v_mfma_f32_16x16x32_bf16 v[36:39], v[222:225], v[186:189], v[36:39]
	v_mfma_f32_16x16x32_bf16 v[28:31], v[210:213], v[194:197], v[28:31]
	v_mfma_f32_16x16x32_bf16 v[20:23], v[222:225], v[194:197], v[20:23]
	v_mfma_f32_16x16x32_bf16 v[12:15], v[210:213], v[202:205], v[12:15]
	v_mfma_f32_16x16x32_bf16 v[4:7], v[222:225], v[202:205], v[4:7]
	s_add_i32 s19, s19, 2
	s_add_u32 s34, s34, 0x100
	s_addc_u32 s35, s35, 0
	s_cmp_gt_u32 s19, 13
	s_cbranch_scc0 .Lrot_232
	s_barrier
	s_lshl_b32 s17, s24, 7
	s_and_b32 s17, s17, 0x400
	s_add_i32 s17, s17, 0x20000
	v_lshl_add_u32 v142, v151, 2, s17
	ds_read_b32 v143, v142
	s_waitcnt lgkmcnt(0)
	v_mul_f32_e32 v144, 0xbfb8aa3b, v143
	v_mul_f32_e32 v164, v143, v143
	ds_read_b32 v143, v142 offset:64
	v_pk_mul_f32 v[160:161], v[120:121], v[144:145] op_sel_hi:[1,0]
	v_pk_mul_f32 v[162:163], v[122:123], v[144:145] op_sel_hi:[1,0]
	v_exp_f32_e32 v160, v160
	v_exp_f32_e32 v161, v161
	v_exp_f32_e32 v162, v162
	v_exp_f32_e32 v163, v163
	v_pk_mul_f32 v[120:121], v[120:121], v[124:125]
	v_pk_add_f32 v[160:161], v[160:161], 1.0 op_sel_hi:[1,0]
	v_pk_mul_f32 v[122:123], v[122:123], v[126:127]
	v_pk_add_f32 v[162:163], v[162:163], 1.0 op_sel_hi:[1,0]
	v_rcp_f32_e32 v160, v160
	v_rcp_f32_e32 v161, v161
	v_rcp_f32_e32 v162, v162
	v_rcp_f32_e32 v163, v163
	v_pk_mul_f32 v[160:161], v[164:165], v[160:161] op_sel_hi:[0,1]
	v_pk_mul_f32 v[120:121], v[120:121], v[160:161]
	v_pk_mul_f32 v[162:163], v[164:165], v[162:163] op_sel_hi:[0,1]
	v_pk_mul_f32 v[122:123], v[122:123], v[162:163]
	v_pk_mul_f32 v[160:161], v[112:113], v[144:145] op_sel_hi:[1,0]
	v_pk_mul_f32 v[162:163], v[114:115], v[144:145] op_sel_hi:[1,0]
	v_exp_f32_e32 v160, v160
	v_exp_f32_e32 v161, v161
	v_exp_f32_e32 v162, v162
	v_exp_f32_e32 v163, v163
	v_pk_mul_f32 v[112:113], v[112:113], v[116:117]
	v_pk_add_f32 v[160:161], v[160:161], 1.0 op_sel_hi:[1,0]
	v_pk_mul_f32 v[114:115], v[114:115], v[118:119]
	v_pk_add_f32 v[162:163], v[162:163], 1.0 op_sel_hi:[1,0]
	v_rcp_f32_e32 v160, v160
	v_rcp_f32_e32 v161, v161
	v_rcp_f32_e32 v162, v162
	v_rcp_f32_e32 v163, v163
	v_pk_mul_f32 v[160:161], v[164:165], v[160:161] op_sel_hi:[0,1]
	v_pk_mul_f32 v[112:113], v[112:113], v[160:161]
	v_pk_mul_f32 v[162:163], v[164:165], v[162:163] op_sel_hi:[0,1]
	v_pk_mul_f32 v[114:115], v[114:115], v[162:163]
	v_cvt_pk_bf16_f32 v124, v120, v121
	v_cvt_pk_bf16_f32 v125, v122, v123
	v_cvt_pk_bf16_f32 v126, v112, v113
	v_cvt_pk_bf16_f32 v127, v114, v115
	v_lshl_add_u32 v112, s24, 8, v129
	v_lshl_or_b32 v114, s60, 7, v150
	v_mov_b64_e32 v[116:117], s[2:3]
	v_ashrrev_i32_e32 v115, 31, v114
	v_mad_i64_i32 v[118:119], s[26:27], v112, s51, v[116:117]
	v_lshlrev_b64 v[114:115], 1, v[114:115]
	v_mov_b32_e32 v112, 0xb0000
	v_mov_b32_e32 v113, 0
	v_lshl_add_u64 v[118:119], v[118:119], 0, v[114:115]
	v_mov_b32_e32 v120, 0x16000
	v_mov_b32_e32 v121, 0
	v_lshl_add_u64 v[122:123], v[118:119], 0, v[112:113]
	s_mov_b32 s60, s16
	s_mov_b32 s24, s18
	global_store_dwordx4 v[118:119], v[124:127], off
	s_waitcnt lgkmcnt(0)
; __device__ __forceinline__ unsigned pk2(float lo, float hi) { unsigned r; asm volatile("v_cvt_pk_bf16_f32 %0, %1, %2" : "=v"(r) : "v"(lo), "v"(hi)); return r; }
; __device__ __forceinline__ unsigned pk2(float lo, float hi) { return f2bf(lo) | (f2bf(hi) << 16); }
;     __device__ __forceinline__ void epi(const f32x4 (&acc)[2][2][4][2], const Unit& u, int wr, int wc, int fr, int fq) const {
;     ...
;             for (int m = 0; m < 4; ++m) {
;                 const int row = row0 + ai * 128 + m * 16; const float rs = rs_lds[((u.pm >> 3) & 1) * 256 + (row & 255)];
;                 const float rs2 = rs * -1.4426950408889634f, rsq = rs * rs;
;                 f32x2 v[4];
; #pragma unroll
;                 for (int n = 0; n < 2; ++n)
; #pragma unroll
;                     for (int jp = 0; jp < 2; ++jp) {
;                         const f32x2 gg = (f32x2){acc[ai][0][m][n][2 * jp], acc[ai][0][m][n][2 * jp + 1]}, uu = (f32x2){acc[ai][1][m][n][2 * jp], acc[ai][1][m][n][2 * jp + 1]};
;                         const f32x2 t = gg * rs2; f32x2 e; e.x = __builtin_amdgcn_exp2f(t.x); e.y = __builtin_amdgcn_exp2f(t.y);
;                         const f32x2 d = e + 1.0f; f32x2 r; r.x = __builtin_amdgcn_rcpf(d.x); r.y = __builtin_amdgcn_rcpf(d.y);
;                         v[n * 2 + jp] = (gg * uu) * (r * rsq);
;                     }
;                 u32x4 w; w.x = pk2(v[0].x, v[0].y); w.y = pk2(v[1].x, v[1].y); w.z = pk2(v[2].x, v[2].y); w.w = pk2(v[3].x, v[3].y);
;                 *(u32x4*)(H + (size_t)row * FF + col0) = w;
	v_mul_f32_e32 v144, 0xbfb8aa3b, v143
	v_mul_f32_e32 v164, v143, v143
	ds_read_b32 v143, v142 offset:128
	v_pk_mul_f32 v[160:161], v[104:105], v[144:145] op_sel_hi:[1,0]
	v_pk_mul_f32 v[162:163], v[106:107], v[144:145] op_sel_hi:[1,0]
	v_exp_f32_e32 v160, v160
	v_exp_f32_e32 v161, v161
	v_exp_f32_e32 v162, v162
	v_exp_f32_e32 v163, v163
	v_pk_mul_f32 v[104:105], v[104:105], v[108:109]
	v_pk_add_f32 v[160:161], v[160:161], 1.0 op_sel_hi:[1,0]
	v_pk_mul_f32 v[106:107], v[106:107], v[110:111]
	v_pk_add_f32 v[162:163], v[162:163], 1.0 op_sel_hi:[1,0]
	v_rcp_f32_e32 v160, v160
	v_rcp_f32_e32 v161, v161
	v_rcp_f32_e32 v162, v162
	v_rcp_f32_e32 v163, v163
	v_pk_mul_f32 v[160:161], v[164:165], v[160:161] op_sel_hi:[0,1]
	v_pk_mul_f32 v[104:105], v[104:105], v[160:161]
	v_pk_mul_f32 v[162:163], v[164:165], v[162:163] op_sel_hi:[0,1]
	v_pk_mul_f32 v[106:107], v[106:107], v[162:163]
	v_pk_mul_f32 v[160:161], v[96:97], v[144:145] op_sel_hi:[1,0]
	v_pk_mul_f32 v[162:163], v[98:99], v[144:145] op_sel_hi:[1,0]
	v_exp_f32_e32 v160, v160
	v_exp_f32_e32 v161, v161
	v_exp_f32_e32 v162, v162
	v_exp_f32_e32 v163, v163
	v_pk_mul_f32 v[96:97], v[96:97], v[100:101]
	v_pk_add_f32 v[160:161], v[160:161], 1.0 op_sel_hi:[1,0]
	v_pk_mul_f32 v[98:99], v[98:99], v[102:103]
	v_pk_add_f32 v[162:163], v[162:163], 1.0 op_sel_hi:[1,0]
	v_rcp_f32_e32 v160, v160
	v_rcp_f32_e32 v161, v161
	v_rcp_f32_e32 v162, v162
	v_rcp_f32_e32 v163, v163
	v_pk_mul_f32 v[160:161], v[164:165], v[160:161] op_sel_hi:[0,1]
	v_pk_mul_f32 v[96:97], v[96:97], v[160:161]
	v_pk_mul_f32 v[162:163], v[164:165], v[162:163] op_sel_hi:[0,1]
	v_pk_mul_f32 v[98:99], v[98:99], v[162:163]
	v_cvt_pk_bf16_f32 v108, v104, v105
	v_cvt_pk_bf16_f32 v109, v106, v107
	v_cvt_pk_bf16_f32 v110, v96, v97
	v_cvt_pk_bf16_f32 v111, v98, v99
	v_lshl_add_u64 v[118:119], v[118:119], 0, v[120:121]
	global_store_dwordx4 v[118:119], v[108:111], off
	s_waitcnt lgkmcnt(0)
	v_mul_f32_e32 v144, 0xbfb8aa3b, v143
	v_mul_f32_e32 v164, v143, v143
	ds_read_b32 v143, v142 offset:192
	v_pk_mul_f32 v[160:161], v[88:89], v[144:145] op_sel_hi:[1,0]
	v_pk_mul_f32 v[162:163], v[90:91], v[144:145] op_sel_hi:[1,0]
	v_exp_f32_e32 v160, v160
	v_exp_f32_e32 v161, v161
	v_exp_f32_e32 v162, v162
	v_exp_f32_e32 v163, v163
	v_pk_mul_f32 v[88:89], v[88:89], v[92:93]
	v_pk_add_f32 v[160:161], v[160:161], 1.0 op_sel_hi:[1,0]
	v_pk_mul_f32 v[90:91], v[90:91], v[94:95]
	v_pk_add_f32 v[162:163], v[162:163], 1.0 op_sel_hi:[1,0]
	v_rcp_f32_e32 v160, v160
	v_rcp_f32_e32 v161, v161
	v_rcp_f32_e32 v162, v162
	v_rcp_f32_e32 v163, v163
	v_pk_mul_f32 v[160:161], v[164:165], v[160:161] op_sel_hi:[0,1]
	v_pk_mul_f32 v[88:89], v[88:89], v[160:161]
	v_pk_mul_f32 v[162:163], v[164:165], v[162:163] op_sel_hi:[0,1]
	v_pk_mul_f32 v[90:91], v[90:91], v[162:163]
	v_pk_mul_f32 v[160:161], v[80:81], v[144:145] op_sel_hi:[1,0]
	v_pk_mul_f32 v[162:163], v[82:83], v[144:145] op_sel_hi:[1,0]
	v_exp_f32_e32 v160, v160
	v_exp_f32_e32 v161, v161
	v_exp_f32_e32 v162, v162
	v_exp_f32_e32 v163, v163
	v_pk_mul_f32 v[80:81], v[80:81], v[84:85]
	v_pk_add_f32 v[160:161], v[160:161], 1.0 op_sel_hi:[1,0]
	v_pk_mul_f32 v[82:83], v[82:83], v[86:87]
	v_pk_add_f32 v[162:163], v[162:163], 1.0 op_sel_hi:[1,0]
	v_rcp_f32_e32 v160, v160
	v_rcp_f32_e32 v161, v161
	v_rcp_f32_e32 v162, v162
	v_rcp_f32_e32 v163, v163
	v_pk_mul_f32 v[160:161], v[164:165], v[160:161] op_sel_hi:[0,1]
	v_pk_mul_f32 v[80:81], v[80:81], v[160:161]
	v_pk_mul_f32 v[162:163], v[164:165], v[162:163] op_sel_hi:[0,1]
	v_pk_mul_f32 v[82:83], v[82:83], v[162:163]
	v_cvt_pk_bf16_f32 v92, v88, v89
	v_cvt_pk_bf16_f32 v93, v90, v91
	v_cvt_pk_bf16_f32 v94, v80, v81
	v_cvt_pk_bf16_f32 v95, v82, v83
	v_lshl_add_u64 v[118:119], v[118:119], 0, v[120:121]
	global_store_dwordx4 v[118:119], v[92:95], off
	s_waitcnt lgkmcnt(0)
	v_mul_f32_e32 v144, 0xbfb8aa3b, v143
	v_mul_f32_e32 v164, v143, v143
	ds_read_b32 v143, v142 offset:512
	v_pk_mul_f32 v[160:161], v[72:73], v[144:145] op_sel_hi:[1,0]
	v_pk_mul_f32 v[162:163], v[74:75], v[144:145] op_sel_hi:[1,0]
	v_exp_f32_e32 v160, v160
	v_exp_f32_e32 v161, v161
	v_exp_f32_e32 v162, v162
	v_exp_f32_e32 v163, v163
	v_pk_mul_f32 v[72:73], v[72:73], v[76:77]
	v_pk_add_f32 v[160:161], v[160:161], 1.0 op_sel_hi:[1,0]
	v_pk_mul_f32 v[74:75], v[74:75], v[78:79]
	v_pk_add_f32 v[162:163], v[162:163], 1.0 op_sel_hi:[1,0]
	v_rcp_f32_e32 v160, v160
	v_rcp_f32_e32 v161, v161
	v_rcp_f32_e32 v162, v162
	v_rcp_f32_e32 v163, v163
	v_pk_mul_f32 v[160:161], v[164:165], v[160:161] op_sel_hi:[0,1]
	v_pk_mul_f32 v[72:73], v[72:73], v[160:161]
	v_pk_mul_f32 v[162:163], v[164:165], v[162:163] op_sel_hi:[0,1]
	v_pk_mul_f32 v[74:75], v[74:75], v[162:163]
	v_pk_mul_f32 v[160:161], v[60:61], v[144:145] op_sel_hi:[1,0]
	v_pk_mul_f32 v[162:163], v[62:63], v[144:145] op_sel_hi:[1,0]
	v_exp_f32_e32 v160, v160
	v_exp_f32_e32 v161, v161
	v_exp_f32_e32 v162, v162
	v_exp_f32_e32 v163, v163
	v_pk_mul_f32 v[60:61], v[60:61], v[64:65]
	v_pk_add_f32 v[160:161], v[160:161], 1.0 op_sel_hi:[1,0]
	v_pk_mul_f32 v[62:63], v[62:63], v[66:67]
	v_pk_add_f32 v[162:163], v[162:163], 1.0 op_sel_hi:[1,0]
	v_rcp_f32_e32 v160, v160
	v_rcp_f32_e32 v161, v161
	v_rcp_f32_e32 v162, v162
	v_rcp_f32_e32 v163, v163
	v_pk_mul_f32 v[160:161], v[164:165], v[160:161] op_sel_hi:[0,1]
	v_pk_mul_f32 v[60:61], v[60:61], v[160:161]
	v_pk_mul_f32 v[162:163], v[164:165], v[162:163] op_sel_hi:[0,1]
	v_pk_mul_f32 v[62:63], v[62:63], v[162:163]
	v_cvt_pk_bf16_f32 v76, v72, v73
	v_cvt_pk_bf16_f32 v77, v74, v75
	v_cvt_pk_bf16_f32 v78, v60, v61
	v_cvt_pk_bf16_f32 v79, v62, v63
	v_lshl_add_u64 v[118:119], v[118:119], 0, v[120:121]
	global_store_dwordx4 v[118:119], v[76:79], off
	s_waitcnt lgkmcnt(0)
; __device__ __forceinline__ unsigned pk2(float lo, float hi) { unsigned r; asm volatile("v_cvt_pk_bf16_f32 %0, %1, %2" : "=v"(r) : "v"(lo), "v"(hi)); return r; }
; __device__ __forceinline__ unsigned pk2(float lo, float hi) { return f2bf(lo) | (f2bf(hi) << 16); }
;     __device__ __forceinline__ void epi(const f32x4 (&acc)[2][2][4][2], const Unit& u, int wr, int wc, int fr, int fq) const {
;     ...
;             for (int m = 0; m < 4; ++m) {
;                 const int row = row0 + ai * 128 + m * 16; const float rs = rs_lds[((u.pm >> 3) & 1) * 256 + (row & 255)];
;                 const float rs2 = rs * -1.4426950408889634f, rsq = rs * rs;
;                 f32x2 v[4];
; #pragma unroll
;                 for (int n = 0; n < 2; ++n)
; #pragma unroll
;                     for (int jp = 0; jp < 2; ++jp) {
;                         const f32x2 gg = (f32x2){acc[ai][0][m][n][2 * jp], acc[ai][0][m][n][2 * jp + 1]}, uu = (f32x2){acc[ai][1][m][n][2 * jp], acc[ai][1][m][n][2 * jp + 1]};
;                         const f32x2 t = gg * rs2; f32x2 e; e.x = __builtin_amdgcn_exp2f(t.x); e.y = __builtin_amdgcn_exp2f(t.y);
;                         const f32x2 d = e + 1.0f; f32x2 r; r.x = __builtin_amdgcn_rcpf(d.x); r.y = __builtin_amdgcn_rcpf(d.y);
;                         v[n * 2 + jp] = (gg * uu) * (r * rsq);
;                     }
;                 u32x4 w; w.x = pk2(v[0].x, v[0].y); w.y = pk2(v[1].x, v[1].y); w.z = pk2(v[2].x, v[2].y); w.w = pk2(v[3].x, v[3].y);
;                 *(u32x4*)(H + (size_t)row * FF + col0) = w;
	v_mul_f32_e32 v144, 0xbfb8aa3b, v143
	v_mul_f32_e32 v164, v143, v143
	ds_read_b32 v143, v142 offset:576
	v_pk_mul_f32 v[160:161], v[56:57], v[144:145] op_sel_hi:[1,0]
	v_pk_mul_f32 v[162:163], v[58:59], v[144:145] op_sel_hi:[1,0]
	v_exp_f32_e32 v160, v160
	v_exp_f32_e32 v161, v161
	v_exp_f32_e32 v162, v162
	v_exp_f32_e32 v163, v163
	v_pk_mul_f32 v[56:57], v[56:57], v[68:69]
	v_pk_add_f32 v[160:161], v[160:161], 1.0 op_sel_hi:[1,0]
	v_pk_mul_f32 v[58:59], v[58:59], v[70:71]
	v_pk_add_f32 v[162:163], v[162:163], 1.0 op_sel_hi:[1,0]
	v_rcp_f32_e32 v160, v160
	v_rcp_f32_e32 v161, v161
	v_rcp_f32_e32 v162, v162
	v_rcp_f32_e32 v163, v163
	v_pk_mul_f32 v[160:161], v[164:165], v[160:161] op_sel_hi:[0,1]
	v_pk_mul_f32 v[56:57], v[56:57], v[160:161]
	v_pk_mul_f32 v[162:163], v[164:165], v[162:163] op_sel_hi:[0,1]
	v_pk_mul_f32 v[58:59], v[58:59], v[162:163]
	v_pk_mul_f32 v[160:161], v[48:49], v[144:145] op_sel_hi:[1,0]
	v_pk_mul_f32 v[162:163], v[50:51], v[144:145] op_sel_hi:[1,0]
	v_exp_f32_e32 v160, v160
	v_exp_f32_e32 v161, v161
	v_exp_f32_e32 v162, v162
	v_exp_f32_e32 v163, v163
	v_pk_mul_f32 v[48:49], v[48:49], v[52:53]
	v_pk_add_f32 v[160:161], v[160:161], 1.0 op_sel_hi:[1,0]
	v_pk_mul_f32 v[50:51], v[50:51], v[54:55]
	v_pk_add_f32 v[162:163], v[162:163], 1.0 op_sel_hi:[1,0]
	v_rcp_f32_e32 v160, v160
	v_rcp_f32_e32 v161, v161
	v_rcp_f32_e32 v162, v162
	v_rcp_f32_e32 v163, v163
	v_pk_mul_f32 v[160:161], v[164:165], v[160:161] op_sel_hi:[0,1]
	v_pk_mul_f32 v[48:49], v[48:49], v[160:161]
	v_pk_mul_f32 v[162:163], v[164:165], v[162:163] op_sel_hi:[0,1]
	v_pk_mul_f32 v[50:51], v[50:51], v[162:163]
	v_cvt_pk_bf16_f32 v68, v56, v57
	v_cvt_pk_bf16_f32 v69, v58, v59
	v_cvt_pk_bf16_f32 v70, v48, v49
	v_cvt_pk_bf16_f32 v71, v50, v51
	v_mov_b64_e32 v[118:119], v[122:123]
	global_store_dwordx4 v[118:119], v[68:71], off
	s_waitcnt lgkmcnt(0)
	v_mul_f32_e32 v144, 0xbfb8aa3b, v143
	v_mul_f32_e32 v164, v143, v143
	ds_read_b32 v143, v142 offset:640
	v_pk_mul_f32 v[160:161], v[40:41], v[144:145] op_sel_hi:[1,0]
	v_pk_mul_f32 v[162:163], v[42:43], v[144:145] op_sel_hi:[1,0]
	v_exp_f32_e32 v160, v160
	v_exp_f32_e32 v161, v161
	v_exp_f32_e32 v162, v162
	v_exp_f32_e32 v163, v163
	v_pk_mul_f32 v[40:41], v[40:41], v[44:45]
	v_pk_add_f32 v[160:161], v[160:161], 1.0 op_sel_hi:[1,0]
	v_pk_mul_f32 v[42:43], v[42:43], v[46:47]
	v_pk_add_f32 v[162:163], v[162:163], 1.0 op_sel_hi:[1,0]
	v_rcp_f32_e32 v160, v160
	v_rcp_f32_e32 v161, v161
	v_rcp_f32_e32 v162, v162
	v_rcp_f32_e32 v163, v163
	v_pk_mul_f32 v[160:161], v[164:165], v[160:161] op_sel_hi:[0,1]
	v_pk_mul_f32 v[40:41], v[40:41], v[160:161]
	v_pk_mul_f32 v[162:163], v[164:165], v[162:163] op_sel_hi:[0,1]
	v_pk_mul_f32 v[42:43], v[42:43], v[162:163]
	v_pk_mul_f32 v[160:161], v[32:33], v[144:145] op_sel_hi:[1,0]
	v_pk_mul_f32 v[162:163], v[34:35], v[144:145] op_sel_hi:[1,0]
	v_exp_f32_e32 v160, v160
	v_exp_f32_e32 v161, v161
	v_exp_f32_e32 v162, v162
	v_exp_f32_e32 v163, v163
	v_pk_mul_f32 v[32:33], v[32:33], v[36:37]
	v_pk_add_f32 v[160:161], v[160:161], 1.0 op_sel_hi:[1,0]
	v_pk_mul_f32 v[34:35], v[34:35], v[38:39]
	v_pk_add_f32 v[162:163], v[162:163], 1.0 op_sel_hi:[1,0]
	v_rcp_f32_e32 v160, v160
	v_rcp_f32_e32 v161, v161
	v_rcp_f32_e32 v162, v162
	v_rcp_f32_e32 v163, v163
	v_pk_mul_f32 v[160:161], v[164:165], v[160:161] op_sel_hi:[0,1]
	v_pk_mul_f32 v[32:33], v[32:33], v[160:161]
	v_pk_mul_f32 v[162:163], v[164:165], v[162:163] op_sel_hi:[0,1]
	v_pk_mul_f32 v[34:35], v[34:35], v[162:163]
	v_cvt_pk_bf16_f32 v44, v40, v41
	v_cvt_pk_bf16_f32 v45, v42, v43
	v_cvt_pk_bf16_f32 v46, v32, v33
	v_cvt_pk_bf16_f32 v47, v34, v35
	v_lshl_add_u64 v[118:119], v[118:119], 0, v[120:121]
	global_store_dwordx4 v[118:119], v[44:47], off
	s_waitcnt lgkmcnt(0)
; __device__ __forceinline__ unsigned pk2(float lo, float hi) { unsigned r; asm volatile("v_cvt_pk_bf16_f32 %0, %1, %2" : "=v"(r) : "v"(lo), "v"(hi)); return r; }
; __device__ __forceinline__ unsigned pk2(float lo, float hi) { return f2bf(lo) | (f2bf(hi) << 16); }
; #define G_WAIT_V(n) asm volatile("s_waitcnt vmcnt(" #n ")" ::: "memory")
; #define G_BAR __builtin_amdgcn_s_barrier()
;     ...
;         p.epi(acc, cur, wr, wc, fr, fq);
;         if (!has_next) break;
;         cur = nxt; cA = nA; cB = nB; cA2 = nA2; cB2 = nB2; ++ui;
;     }
;     G_WAIT_V(0);
;     if (wr == 0) G_BAR;
;     G_BAR;
;     __device__ __forceinline__ void epi(const f32x4 (&acc)[2][2][4][2], const Unit& u, int wr, int wc, int fr, int fq) const {
;     ...
;             for (int m = 0; m < 4; ++m) {
;                 const int row = row0 + ai * 128 + m * 16; const float rs = rs_lds[((u.pm >> 3) & 1) * 256 + (row & 255)];
;                 const float rs2 = rs * -1.4426950408889634f, rsq = rs * rs;
;                 f32x2 v[4];
; #pragma unroll
;                 for (int n = 0; n < 2; ++n)
; #pragma unroll
;                     for (int jp = 0; jp < 2; ++jp) {
;                         const f32x2 gg = (f32x2){acc[ai][0][m][n][2 * jp], acc[ai][0][m][n][2 * jp + 1]}, uu = (f32x2){acc[ai][1][m][n][2 * jp], acc[ai][1][m][n][2 * jp + 1]};
;                         const f32x2 t = gg * rs2; f32x2 e; e.x = __builtin_amdgcn_exp2f(t.x); e.y = __builtin_amdgcn_exp2f(t.y);
;                         const f32x2 d = e + 1.0f; f32x2 r; r.x = __builtin_amdgcn_rcpf(d.x); r.y = __builtin_amdgcn_rcpf(d.y);
;                         v[n * 2 + jp] = (gg * uu) * (r * rsq);
;                     }
;                 u32x4 w; w.x = pk2(v[0].x, v[0].y); w.y = pk2(v[1].x, v[1].y); w.z = pk2(v[2].x, v[2].y); w.w = pk2(v[3].x, v[3].y);
;                 *(u32x4*)(H + (size_t)row * FF + col0) = w;
	v_mul_f32_e32 v144, 0xbfb8aa3b, v143
	v_mul_f32_e32 v164, v143, v143
	ds_read_b32 v143, v142 offset:704
	v_pk_mul_f32 v[160:161], v[24:25], v[144:145] op_sel_hi:[1,0]
	v_pk_mul_f32 v[162:163], v[26:27], v[144:145] op_sel_hi:[1,0]
	v_exp_f32_e32 v160, v160
	v_exp_f32_e32 v161, v161
	v_exp_f32_e32 v162, v162
	v_exp_f32_e32 v163, v163
	v_pk_mul_f32 v[24:25], v[24:25], v[28:29]
	v_pk_add_f32 v[160:161], v[160:161], 1.0 op_sel_hi:[1,0]
	v_pk_mul_f32 v[26:27], v[26:27], v[30:31]
	v_pk_add_f32 v[162:163], v[162:163], 1.0 op_sel_hi:[1,0]
	v_rcp_f32_e32 v160, v160
	v_rcp_f32_e32 v161, v161
	v_rcp_f32_e32 v162, v162
	v_rcp_f32_e32 v163, v163
	v_pk_mul_f32 v[160:161], v[164:165], v[160:161] op_sel_hi:[0,1]
	v_pk_mul_f32 v[24:25], v[24:25], v[160:161]
	v_pk_mul_f32 v[162:163], v[164:165], v[162:163] op_sel_hi:[0,1]
	v_pk_mul_f32 v[26:27], v[26:27], v[162:163]
	v_pk_mul_f32 v[160:161], v[16:17], v[144:145] op_sel_hi:[1,0]
	v_pk_mul_f32 v[162:163], v[18:19], v[144:145] op_sel_hi:[1,0]
	v_exp_f32_e32 v160, v160
	v_exp_f32_e32 v161, v161
	v_exp_f32_e32 v162, v162
	v_exp_f32_e32 v163, v163
	v_pk_mul_f32 v[16:17], v[16:17], v[20:21]
	v_pk_add_f32 v[160:161], v[160:161], 1.0 op_sel_hi:[1,0]
	v_pk_mul_f32 v[18:19], v[18:19], v[22:23]
	v_pk_add_f32 v[162:163], v[162:163], 1.0 op_sel_hi:[1,0]
	v_rcp_f32_e32 v160, v160
	v_rcp_f32_e32 v161, v161
	v_rcp_f32_e32 v162, v162
	v_rcp_f32_e32 v163, v163
	v_pk_mul_f32 v[160:161], v[164:165], v[160:161] op_sel_hi:[0,1]
	v_pk_mul_f32 v[16:17], v[16:17], v[160:161]
	v_pk_mul_f32 v[162:163], v[164:165], v[162:163] op_sel_hi:[0,1]
	v_pk_mul_f32 v[18:19], v[18:19], v[162:163]
	v_cvt_pk_bf16_f32 v28, v24, v25
	v_cvt_pk_bf16_f32 v29, v26, v27
	v_cvt_pk_bf16_f32 v30, v16, v17
	v_cvt_pk_bf16_f32 v31, v18, v19
	v_lshl_add_u64 v[118:119], v[118:119], 0, v[120:121]
	global_store_dwordx4 v[118:119], v[28:31], off
	s_waitcnt lgkmcnt(0)
	v_mul_f32_e32 v144, 0xbfb8aa3b, v143
	v_mul_f32_e32 v164, v143, v143
	v_pk_mul_f32 v[160:161], v[8:9], v[144:145] op_sel_hi:[1,0]
	v_pk_mul_f32 v[162:163], v[10:11], v[144:145] op_sel_hi:[1,0]
	v_exp_f32_e32 v160, v160
	v_exp_f32_e32 v161, v161
	v_exp_f32_e32 v162, v162
	v_exp_f32_e32 v163, v163
	v_pk_mul_f32 v[8:9], v[8:9], v[12:13]
	v_pk_add_f32 v[160:161], v[160:161], 1.0 op_sel_hi:[1,0]
	v_pk_mul_f32 v[10:11], v[10:11], v[14:15]
	v_pk_add_f32 v[162:163], v[162:163], 1.0 op_sel_hi:[1,0]
	v_rcp_f32_e32 v160, v160
	v_rcp_f32_e32 v161, v161
	v_rcp_f32_e32 v162, v162
	v_rcp_f32_e32 v163, v163
	v_pk_mul_f32 v[160:161], v[164:165], v[160:161] op_sel_hi:[0,1]
	v_pk_mul_f32 v[8:9], v[8:9], v[160:161]
	v_pk_mul_f32 v[162:163], v[164:165], v[162:163] op_sel_hi:[0,1]
	v_pk_mul_f32 v[10:11], v[10:11], v[162:163]
	v_pk_mul_f32 v[160:161], v[0:1], v[144:145] op_sel_hi:[1,0]
	v_pk_mul_f32 v[162:163], v[2:3], v[144:145] op_sel_hi:[1,0]
	v_exp_f32_e32 v160, v160
	v_exp_f32_e32 v161, v161
	v_exp_f32_e32 v162, v162
	v_exp_f32_e32 v163, v163
	v_pk_mul_f32 v[0:1], v[0:1], v[4:5]
	v_pk_add_f32 v[160:161], v[160:161], 1.0 op_sel_hi:[1,0]
	v_pk_mul_f32 v[2:3], v[2:3], v[6:7]
	v_pk_add_f32 v[162:163], v[162:163], 1.0 op_sel_hi:[1,0]
	v_rcp_f32_e32 v160, v160
	v_rcp_f32_e32 v161, v161
	v_rcp_f32_e32 v162, v162
	v_rcp_f32_e32 v163, v163
	v_pk_mul_f32 v[160:161], v[164:165], v[160:161] op_sel_hi:[0,1]
	v_pk_mul_f32 v[0:1], v[0:1], v[160:161]
	v_pk_mul_f32 v[162:163], v[164:165], v[162:163] op_sel_hi:[0,1]
	v_pk_mul_f32 v[2:3], v[2:3], v[162:163]
	v_cvt_pk_bf16_f32 v12, v8, v9
	v_cvt_pk_bf16_f32 v13, v10, v11
	v_cvt_pk_bf16_f32 v14, v0, v1
	v_cvt_pk_bf16_f32 v15, v2, v3
	v_lshl_add_u64 v[118:119], v[118:119], 0, v[120:121]
	global_store_dwordx4 v[118:119], v[12:15], off
	s_mov_b64 s[28:29], s[22:23]
	s_mov_b64 s[26:27], s[20:21]
	s_and_b64 vcc, exec, s[14:15]
	s_cbranch_vccz .LBB0_229
	s_waitcnt vmcnt(0)
	s_cmpk_gt_u32 s38, 0xff
	s_cbranch_scc1 .LBB0_236
	s_barrier
